# v34 plus grid barrier: local workgroups poll the cross-XCD release word directly (one hop less)
# speedup vs baseline: 1.0127x; 1.0093x over previous
; __device__ __forceinline__ unsigned xb_ld(unsigned* p)              { return __hip_atomic_load(p, __ATOMIC_RELAXED, __HIP_MEMORY_SCOPE_AGENT); }
; __device__ __forceinline__ unsigned xb_add(unsigned* p, unsigned v) { return __hip_atomic_fetch_add(p, v, __ATOMIC_RELAXED, __HIP_MEMORY_SCOPE_AGENT); }
; #define XB_SPIN(cond, bar) do { unsigned _sp = 0; while (cond) { __builtin_amdgcn_s_sleep(1); \
;     if ((++_sp & 255u) == 0u) { if (xb_ld(&(bar)[XB_TMO])) break; if (_sp > XB_SPIN_CAP) { atomicAdd(&(bar)[XB_TMO], 1u); break; } } } } while (0)
; __device__ __forceinline__ void xcd_barrier(const XcdBarrier& b) {
;     ...
;         const unsigned old = xb_add(&bar[XB_XSUB(b.x)], 1u);
;         const unsigned gen = old / nloc;
;         if (old + 1u == (gen + 1u) * nloc) {
;             __builtin_amdgcn_fence(__ATOMIC_RELEASE, "agent");
;             asm volatile("s_waitcnt vmcnt(0)" ::: "memory");
;             const unsigned og = xb_add(&bar[XB_TOP], 1u);
;             const unsigned tg = og / nx;
;             if (og + 1u == (tg + 1u) * nx) xb_add(&bar[XB_TOPGEN], 1u);
;             else XB_SPIN(xb_ld(&bar[XB_TOPGEN]) == tg, bar);
;             __builtin_amdgcn_fence(__ATOMIC_ACQUIRE, "agent");
;             xb_add(&bar[XB_XGEN(b.x)], 1u);
;             asm volatile("s_waitcnt vmcnt(0)" ::: "memory");
;         } else {
;             XB_SPIN(xb_ld(&bar[XB_XGEN(b.x)]) == gen, bar);
.LBB0_201:
	s_or_b64 exec, exec, s[14:15]
	v_cvt_f32_u32_e32 v4, v2
	s_waitcnt vmcnt(0)
	v_readfirstlane_b32 s1, v3
	v_sub_u32_e32 v3, 0, v2
	v_rcp_iflag_f32_e32 v4, v4
	v_add_u32_e32 v5, s1, v1
	v_mul_f32_e32 v4, 0x4f7ffffe, v4
	v_cvt_u32_f32_e32 v4, v4
	v_mul_lo_u32 v1, v3, v4
	v_mul_hi_u32 v1, v4, v1
	v_add_u32_e32 v1, v4, v1
	v_mul_hi_u32 v1, v5, v1
	v_mul_lo_u32 v3, v1, v2
	v_sub_u32_e32 v3, v5, v3
	v_add_u32_e32 v4, 1, v1
	v_cmp_ge_u32_e32 vcc, v3, v2
	s_nop 1
	v_cndmask_b32_e32 v1, v1, v4, vcc
	v_sub_u32_e32 v4, v3, v2
	v_cndmask_b32_e32 v3, v3, v4, vcc
	v_add_u32_e32 v4, 1, v1
	v_cmp_ge_u32_e32 vcc, v3, v2
	v_add_u32_e32 v3, 1, v5
	s_nop 0
	v_cndmask_b32_e32 v1, v1, v4, vcc
	v_mul_lo_u32 v4, v2, v1
	v_add_u32_e32 v2, v4, v2
	v_cmp_ne_u32_e32 vcc, v3, v2
	s_and_saveexec_b64 s[6:7], vcc
	s_xor_b64 s[12:13], exec, s[6:7]
	s_cbranch_execz .LBB0_215
	s_waitcnt lgkmcnt(0)
	v_mov_b32_e32 v0, 0x7000
	global_load_dword v0, v0, s[8:9] offset:1280 sc1
	s_add_u32 s18, s8, 0x7500
	s_addc_u32 s19, s9, 0
	s_waitcnt vmcnt(0)
	v_cmp_eq_u32_e32 vcc, v0, v1
	s_and_saveexec_b64 s[14:15], vcc
	s_cbranch_execz .LBB0_214
	s_add_u32 s16, s8, 0x4200
	s_addc_u32 s17, s9, 0
	s_mov_b32 s1, 1
	s_mov_b64 s[22:23], 0
	v_mov_b32_e32 v0, 0
	s_branch .LBB0_205

; __device__ __forceinline__ unsigned xb_ld(unsigned* p)              { return __hip_atomic_load(p, __ATOMIC_RELAXED, __HIP_MEMORY_SCOPE_AGENT); }
; __device__ __forceinline__ unsigned xb_add(unsigned* p, unsigned v) { return __hip_atomic_fetch_add(p, v, __ATOMIC_RELAXED, __HIP_MEMORY_SCOPE_AGENT); }
; #define XB_SPIN(cond, bar) do { unsigned _sp = 0; while (cond) { __builtin_amdgcn_s_sleep(1); \
;     if ((++_sp & 255u) == 0u) { if (xb_ld(&(bar)[XB_TMO])) break; if (_sp > XB_SPIN_CAP) { atomicAdd(&(bar)[XB_TMO], 1u); break; } } } } while (0)
; __device__ __forceinline__ void xcd_barrier(const XcdBarrier& b) {
;     ...
;         const unsigned old = xb_add(&bar[XB_XSUB(b.x)], 1u);
;         const unsigned gen = old / nloc;
;         if (old + 1u == (gen + 1u) * nloc) {
;             __builtin_amdgcn_fence(__ATOMIC_RELEASE, "agent");
;             asm volatile("s_waitcnt vmcnt(0)" ::: "memory");
;             const unsigned og = xb_add(&bar[XB_TOP], 1u);
;             const unsigned tg = og / nx;
;             if (og + 1u == (tg + 1u) * nx) xb_add(&bar[XB_TOPGEN], 1u);
;             else XB_SPIN(xb_ld(&bar[XB_TOPGEN]) == tg, bar);
;             __builtin_amdgcn_fence(__ATOMIC_ACQUIRE, "agent");
;             xb_add(&bar[XB_XGEN(b.x)], 1u);
;             asm volatile("s_waitcnt vmcnt(0)" ::: "memory");
;         } else {
;             XB_SPIN(xb_ld(&bar[XB_XGEN(b.x)]) == gen, bar);
.LBB0_265:
	s_or_b64 exec, exec, s[18:19]
	v_cvt_f32_u32_e32 v4, v2
	s_waitcnt vmcnt(0)
	v_readfirstlane_b32 s1, v3
	v_sub_u32_e32 v3, 0, v2
	v_rcp_iflag_f32_e32 v4, v4
	v_add_u32_e32 v5, s1, v1
	v_mul_f32_e32 v4, 0x4f7ffffe, v4
	v_cvt_u32_f32_e32 v4, v4
	v_mul_lo_u32 v1, v3, v4
	v_mul_hi_u32 v1, v4, v1
	v_add_u32_e32 v1, v4, v1
	v_mul_hi_u32 v1, v5, v1
	v_mul_lo_u32 v3, v1, v2
	v_sub_u32_e32 v3, v5, v3
	v_add_u32_e32 v4, 1, v1
	v_cmp_ge_u32_e32 vcc, v3, v2
	s_nop 1
	v_cndmask_b32_e32 v1, v1, v4, vcc
	v_sub_u32_e32 v4, v3, v2
	v_cndmask_b32_e32 v3, v3, v4, vcc
	v_add_u32_e32 v4, 1, v1
	v_cmp_ge_u32_e32 vcc, v3, v2
	v_add_u32_e32 v3, 1, v5
	s_nop 0
	v_cndmask_b32_e32 v1, v1, v4, vcc
	v_mul_lo_u32 v4, v2, v1
	v_add_u32_e32 v2, v4, v2
	v_cmp_ne_u32_e32 vcc, v3, v2
	s_and_saveexec_b64 s[14:15], vcc
	s_xor_b64 s[14:15], exec, s[14:15]
	s_cbranch_execz .LBB0_279
	s_waitcnt lgkmcnt(0)
	v_mov_b32_e32 v0, 0x7000
	global_load_dword v0, v0, s[10:11] offset:1280 sc1
	s_add_u32 s24, s10, 0x7500
	s_addc_u32 s25, s11, 0
	s_waitcnt vmcnt(0)
	v_cmp_eq_u32_e32 vcc, v0, v1
	s_and_saveexec_b64 s[18:19], vcc
	s_cbranch_execz .LBB0_278
	s_add_u32 s22, s10, 0x4200
	s_addc_u32 s23, s11, 0
	s_mov_b32 s1, 1
	s_mov_b64 s[26:27], 0
	v_mov_b32_e32 v0, 0
	s_branch .LBB0_269

; __device__ __forceinline__ unsigned xb_ld(unsigned* p)              { return __hip_atomic_load(p, __ATOMIC_RELAXED, __HIP_MEMORY_SCOPE_AGENT); }
; __device__ __forceinline__ unsigned xb_add(unsigned* p, unsigned v) { return __hip_atomic_fetch_add(p, v, __ATOMIC_RELAXED, __HIP_MEMORY_SCOPE_AGENT); }
; #define XB_SPIN(cond, bar) do { unsigned _sp = 0; while (cond) { __builtin_amdgcn_s_sleep(1); \
;     if ((++_sp & 255u) == 0u) { if (xb_ld(&(bar)[XB_TMO])) break; if (_sp > XB_SPIN_CAP) { atomicAdd(&(bar)[XB_TMO], 1u); break; } } } } while (0)
; __device__ __forceinline__ void xcd_barrier(const XcdBarrier& b) {
;     ...
;         const unsigned old = xb_add(&bar[XB_XSUB(b.x)], 1u);
;         const unsigned gen = old / nloc;
;         if (old + 1u == (gen + 1u) * nloc) {
;             __builtin_amdgcn_fence(__ATOMIC_RELEASE, "agent");
;             asm volatile("s_waitcnt vmcnt(0)" ::: "memory");
;             const unsigned og = xb_add(&bar[XB_TOP], 1u);
;             const unsigned tg = og / nx;
;             if (og + 1u == (tg + 1u) * nx) xb_add(&bar[XB_TOPGEN], 1u);
;             else XB_SPIN(xb_ld(&bar[XB_TOPGEN]) == tg, bar);
;             __builtin_amdgcn_fence(__ATOMIC_ACQUIRE, "agent");
;             xb_add(&bar[XB_XGEN(b.x)], 1u);
;             asm volatile("s_waitcnt vmcnt(0)" ::: "memory");
;         } else {
;             XB_SPIN(xb_ld(&bar[XB_XGEN(b.x)]) == gen, bar);
.LBB0_477:
	s_or_b64 exec, exec, s[18:19]
	v_cvt_f32_u32_e32 v4, v2
	s_waitcnt vmcnt(0)
	v_readfirstlane_b32 s1, v3
	v_sub_u32_e32 v3, 0, v2
	v_rcp_iflag_f32_e32 v4, v4
	v_add_u32_e32 v5, s1, v1
	v_mul_f32_e32 v4, 0x4f7ffffe, v4
	v_cvt_u32_f32_e32 v4, v4
	v_mul_lo_u32 v1, v3, v4
	v_mul_hi_u32 v1, v4, v1
	v_add_u32_e32 v1, v4, v1
	v_mul_hi_u32 v1, v5, v1
	v_mul_lo_u32 v3, v1, v2
	v_sub_u32_e32 v3, v5, v3
	v_add_u32_e32 v4, 1, v1
	v_cmp_ge_u32_e32 vcc, v3, v2
	s_nop 1
	v_cndmask_b32_e32 v1, v1, v4, vcc
	v_sub_u32_e32 v4, v3, v2
	v_cndmask_b32_e32 v3, v3, v4, vcc
	v_add_u32_e32 v4, 1, v1
	v_cmp_ge_u32_e32 vcc, v3, v2
	v_add_u32_e32 v3, 1, v5
	s_nop 0
	v_cndmask_b32_e32 v1, v1, v4, vcc
	v_mul_lo_u32 v4, v2, v1
	v_add_u32_e32 v2, v4, v2
	v_cmp_ne_u32_e32 vcc, v3, v2
	s_and_saveexec_b64 s[4:5], vcc
	s_xor_b64 s[16:17], exec, s[4:5]
	s_cbranch_execz .LBB0_491
	s_waitcnt lgkmcnt(0)
	v_mov_b32_e32 v0, 0x7000
	global_load_dword v0, v0, s[12:13] offset:1280 sc1
	s_add_u32 s24, s12, 0x7500
	s_addc_u32 s25, s13, 0
	s_waitcnt vmcnt(0)
	v_cmp_eq_u32_e32 vcc, v0, v1
	s_and_saveexec_b64 s[18:19], vcc
	s_cbranch_execz .LBB0_490
	s_add_u32 s22, s12, 0x4200
	s_addc_u32 s23, s13, 0
	s_mov_b32 s1, 1
	s_mov_b64 s[26:27], 0
	v_mov_b32_e32 v0, 0
	s_branch .LBB0_481

; __device__ __forceinline__ unsigned xb_ld(unsigned* p)              { return __hip_atomic_load(p, __ATOMIC_RELAXED, __HIP_MEMORY_SCOPE_AGENT); }
; __device__ __forceinline__ unsigned xb_add(unsigned* p, unsigned v) { return __hip_atomic_fetch_add(p, v, __ATOMIC_RELAXED, __HIP_MEMORY_SCOPE_AGENT); }
; #define XB_SPIN(cond, bar) do { unsigned _sp = 0; while (cond) { __builtin_amdgcn_s_sleep(1); \
;     if ((++_sp & 255u) == 0u) { if (xb_ld(&(bar)[XB_TMO])) break; if (_sp > XB_SPIN_CAP) { atomicAdd(&(bar)[XB_TMO], 1u); break; } } } } while (0)
; __device__ __forceinline__ void xcd_barrier(const XcdBarrier& b) {
;     ...
;         const unsigned old = xb_add(&bar[XB_XSUB(b.x)], 1u);
;         const unsigned gen = old / nloc;
;         if (old + 1u == (gen + 1u) * nloc) {
;             __builtin_amdgcn_fence(__ATOMIC_RELEASE, "agent");
;             asm volatile("s_waitcnt vmcnt(0)" ::: "memory");
;             const unsigned og = xb_add(&bar[XB_TOP], 1u);
;             const unsigned tg = og / nx;
;             if (og + 1u == (tg + 1u) * nx) xb_add(&bar[XB_TOPGEN], 1u);
;             else XB_SPIN(xb_ld(&bar[XB_TOPGEN]) == tg, bar);
;             __builtin_amdgcn_fence(__ATOMIC_ACQUIRE, "agent");
;             xb_add(&bar[XB_XGEN(b.x)], 1u);
;             asm volatile("s_waitcnt vmcnt(0)" ::: "memory");
;         } else {
;             XB_SPIN(xb_ld(&bar[XB_XGEN(b.x)]) == gen, bar);
.LBB0_753:
	s_or_b64 exec, exec, s[20:21]
	v_cvt_f32_u32_e32 v4, v2
	s_waitcnt vmcnt(0)
	v_readfirstlane_b32 s1, v3
	v_sub_u32_e32 v3, 0, v2
	v_rcp_iflag_f32_e32 v4, v4
	v_add_u32_e32 v5, s1, v1
	v_mul_f32_e32 v4, 0x4f7ffffe, v4
	v_cvt_u32_f32_e32 v4, v4
	v_mul_lo_u32 v1, v3, v4
	v_mul_hi_u32 v1, v4, v1
	v_add_u32_e32 v1, v4, v1
	v_mul_hi_u32 v1, v5, v1
	v_mul_lo_u32 v3, v1, v2
	v_sub_u32_e32 v3, v5, v3
	v_add_u32_e32 v4, 1, v1
	v_cmp_ge_u32_e32 vcc, v3, v2
	s_nop 1
	v_cndmask_b32_e32 v1, v1, v4, vcc
	v_sub_u32_e32 v4, v3, v2
	v_cndmask_b32_e32 v3, v3, v4, vcc
	v_add_u32_e32 v4, 1, v1
	v_cmp_ge_u32_e32 vcc, v3, v2
	v_add_u32_e32 v3, 1, v5
	s_nop 0
	v_cndmask_b32_e32 v1, v1, v4, vcc
	v_mul_lo_u32 v4, v2, v1
	v_add_u32_e32 v2, v4, v2
	v_cmp_ne_u32_e32 vcc, v3, v2
	s_and_saveexec_b64 s[4:5], vcc
	s_xor_b64 s[18:19], exec, s[4:5]
	s_cbranch_execz .LBB0_767
	s_waitcnt lgkmcnt(0)
	v_mov_b32_e32 v0, 0x7000
	global_load_dword v0, v0, s[12:13] offset:1280 sc1
	s_add_u32 s24, s12, 0x7500
	s_addc_u32 s25, s13, 0
	s_waitcnt vmcnt(0)
	v_cmp_eq_u32_e32 vcc, v0, v1
	s_and_saveexec_b64 s[20:21], vcc
	s_cbranch_execz .LBB0_766
	s_add_u32 s22, s12, 0x4200
	s_addc_u32 s23, s13, 0
	s_mov_b32 s1, 1
	s_mov_b64 s[26:27], 0
	v_mov_b32_e32 v0, 0
	s_branch .LBB0_757

; __device__ __forceinline__ unsigned xb_ld(unsigned* p)              { return __hip_atomic_load(p, __ATOMIC_RELAXED, __HIP_MEMORY_SCOPE_AGENT); }
; __device__ __forceinline__ unsigned xb_add(unsigned* p, unsigned v) { return __hip_atomic_fetch_add(p, v, __ATOMIC_RELAXED, __HIP_MEMORY_SCOPE_AGENT); }
; #define XB_SPIN(cond, bar) do { unsigned _sp = 0; while (cond) { __builtin_amdgcn_s_sleep(1); \
;     if ((++_sp & 255u) == 0u) { if (xb_ld(&(bar)[XB_TMO])) break; if (_sp > XB_SPIN_CAP) { atomicAdd(&(bar)[XB_TMO], 1u); break; } } } } while (0)
; __device__ __forceinline__ void xcd_barrier(const XcdBarrier& b) {
;     ...
;         const unsigned old = xb_add(&bar[XB_XSUB(b.x)], 1u);
;         const unsigned gen = old / nloc;
;         if (old + 1u == (gen + 1u) * nloc) {
;             __builtin_amdgcn_fence(__ATOMIC_RELEASE, "agent");
;             asm volatile("s_waitcnt vmcnt(0)" ::: "memory");
;             const unsigned og = xb_add(&bar[XB_TOP], 1u);
;             const unsigned tg = og / nx;
;             if (og + 1u == (tg + 1u) * nx) xb_add(&bar[XB_TOPGEN], 1u);
;             else XB_SPIN(xb_ld(&bar[XB_TOPGEN]) == tg, bar);
;             __builtin_amdgcn_fence(__ATOMIC_ACQUIRE, "agent");
;             xb_add(&bar[XB_XGEN(b.x)], 1u);
;             asm volatile("s_waitcnt vmcnt(0)" ::: "memory");
;         } else {
;             XB_SPIN(xb_ld(&bar[XB_XGEN(b.x)]) == gen, bar);
.LBB0_859:
	s_or_b64 exec, exec, s[22:23]
	v_cvt_f32_u32_e32 v4, v2
	s_waitcnt vmcnt(0)
	v_readfirstlane_b32 s0, v3
	v_sub_u32_e32 v3, 0, v2
	v_rcp_iflag_f32_e32 v4, v4
	v_add_u32_e32 v5, s0, v1
	v_mul_f32_e32 v4, 0x4f7ffffe, v4
	v_cvt_u32_f32_e32 v4, v4
	v_mul_lo_u32 v1, v3, v4
	v_mul_hi_u32 v1, v4, v1
	v_add_u32_e32 v1, v4, v1
	v_mul_hi_u32 v1, v5, v1
	v_mul_lo_u32 v3, v1, v2
	v_sub_u32_e32 v3, v5, v3
	v_add_u32_e32 v4, 1, v1
	v_cmp_ge_u32_e32 vcc, v3, v2
	s_nop 1
	v_cndmask_b32_e32 v1, v1, v4, vcc
	v_sub_u32_e32 v4, v3, v2
	v_cndmask_b32_e32 v3, v3, v4, vcc
	v_add_u32_e32 v4, 1, v1
	v_cmp_ge_u32_e32 vcc, v3, v2
	v_add_u32_e32 v3, 1, v5
	s_nop 0
	v_cndmask_b32_e32 v1, v1, v4, vcc
	v_mul_lo_u32 v4, v2, v1
	v_add_u32_e32 v2, v4, v2
	v_cmp_ne_u32_e32 vcc, v3, v2
	s_and_saveexec_b64 s[14:15], vcc
	s_xor_b64 s[20:21], exec, s[14:15]
	s_cbranch_execz .LBB0_873
	s_waitcnt lgkmcnt(0)
	v_mov_b32_e32 v0, 0x7000
	global_load_dword v0, v0, s[16:17] offset:1280 sc1
	s_add_u32 s26, s16, 0x7500
	s_addc_u32 s27, s17, 0
	s_waitcnt vmcnt(0)
	v_cmp_eq_u32_e32 vcc, v0, v1
	s_and_saveexec_b64 s[22:23], vcc
	s_cbranch_execz .LBB0_872
	s_add_u32 s24, s16, 0x4200
	s_addc_u32 s25, s17, 0
	s_mov_b32 s0, 1
	s_mov_b64 s[44:45], 0
	v_mov_b32_e32 v0, 0
	s_branch .LBB0_863

; __device__ __forceinline__ unsigned xb_ld(unsigned* p)              { return __hip_atomic_load(p, __ATOMIC_RELAXED, __HIP_MEMORY_SCOPE_AGENT); }
; __device__ __forceinline__ unsigned xb_add(unsigned* p, unsigned v) { return __hip_atomic_fetch_add(p, v, __ATOMIC_RELAXED, __HIP_MEMORY_SCOPE_AGENT); }
; #define XB_SPIN(cond, bar) do { unsigned _sp = 0; while (cond) { __builtin_amdgcn_s_sleep(1); \
;     if ((++_sp & 255u) == 0u) { if (xb_ld(&(bar)[XB_TMO])) break; if (_sp > XB_SPIN_CAP) { atomicAdd(&(bar)[XB_TMO], 1u); break; } } } } while (0)
; __device__ __forceinline__ void xcd_barrier(const XcdBarrier& b) {
;     ...
;         const unsigned old = xb_add(&bar[XB_XSUB(b.x)], 1u);
;         const unsigned gen = old / nloc;
;         if (old + 1u == (gen + 1u) * nloc) {
;             __builtin_amdgcn_fence(__ATOMIC_RELEASE, "agent");
;             asm volatile("s_waitcnt vmcnt(0)" ::: "memory");
;             const unsigned og = xb_add(&bar[XB_TOP], 1u);
;             const unsigned tg = og / nx;
;             if (og + 1u == (tg + 1u) * nx) xb_add(&bar[XB_TOPGEN], 1u);
;             else XB_SPIN(xb_ld(&bar[XB_TOPGEN]) == tg, bar);
;             __builtin_amdgcn_fence(__ATOMIC_ACQUIRE, "agent");
;             xb_add(&bar[XB_XGEN(b.x)], 1u);
;             asm volatile("s_waitcnt vmcnt(0)" ::: "memory");
;         } else {
;             XB_SPIN(xb_ld(&bar[XB_XGEN(b.x)]) == gen, bar);
.LBB0_1021:
	s_or_b64 exec, exec, s[24:25]
	v_cvt_f32_u32_e32 v4, v2
	s_waitcnt vmcnt(0)
	v_readfirstlane_b32 s0, v3
	v_sub_u32_e32 v3, 0, v2
	v_rcp_iflag_f32_e32 v4, v4
	v_add_u32_e32 v5, s0, v1
	v_mul_f32_e32 v4, 0x4f7ffffe, v4
	v_cvt_u32_f32_e32 v4, v4
	v_mul_lo_u32 v1, v3, v4
	v_mul_hi_u32 v1, v4, v1
	v_add_u32_e32 v1, v4, v1
	v_mul_hi_u32 v1, v5, v1
	v_mul_lo_u32 v3, v1, v2
	v_sub_u32_e32 v3, v5, v3
	v_add_u32_e32 v4, 1, v1
	v_cmp_ge_u32_e32 vcc, v3, v2
	s_nop 1
	v_cndmask_b32_e32 v1, v1, v4, vcc
	v_sub_u32_e32 v4, v3, v2
	v_cndmask_b32_e32 v3, v3, v4, vcc
	v_add_u32_e32 v4, 1, v1
	v_cmp_ge_u32_e32 vcc, v3, v2
	v_add_u32_e32 v3, 1, v5
	s_nop 0
	v_cndmask_b32_e32 v1, v1, v4, vcc
	v_mul_lo_u32 v4, v2, v1
	v_add_u32_e32 v2, v4, v2
	v_cmp_ne_u32_e32 vcc, v3, v2
	s_and_saveexec_b64 s[12:13], vcc
	s_xor_b64 s[22:23], exec, s[12:13]
	s_cbranch_execz .LBB0_1035
	s_waitcnt lgkmcnt(0)
	v_mov_b32_e32 v0, 0x7000
	global_load_dword v0, v0, s[18:19] offset:1280 sc1
	s_add_u32 s42, s18, 0x7500
	s_addc_u32 s43, s19, 0
	s_waitcnt vmcnt(0)
	v_cmp_eq_u32_e32 vcc, v0, v1
	s_and_saveexec_b64 s[24:25], vcc
	s_cbranch_execz .LBB0_1034
	s_add_u32 s26, s18, 0x4200
	s_addc_u32 s27, s19, 0
	s_mov_b32 s0, 1
	s_mov_b64 s[44:45], 0
	v_mov_b32_e32 v0, 0
	s_branch .LBB0_1025

; __device__ __forceinline__ unsigned xb_ld(unsigned* p)              { return __hip_atomic_load(p, __ATOMIC_RELAXED, __HIP_MEMORY_SCOPE_AGENT); }
; __device__ __forceinline__ unsigned xb_add(unsigned* p, unsigned v) { return __hip_atomic_fetch_add(p, v, __ATOMIC_RELAXED, __HIP_MEMORY_SCOPE_AGENT); }
; #define XB_SPIN(cond, bar) do { unsigned _sp = 0; while (cond) { __builtin_amdgcn_s_sleep(1); \
;     if ((++_sp & 255u) == 0u) { if (xb_ld(&(bar)[XB_TMO])) break; if (_sp > XB_SPIN_CAP) { atomicAdd(&(bar)[XB_TMO], 1u); break; } } } } while (0)
; __device__ __forceinline__ void xcd_barrier(const XcdBarrier& b) {
;     ...
;         const unsigned old = xb_add(&bar[XB_XSUB(b.x)], 1u);
;         const unsigned gen = old / nloc;
;         if (old + 1u == (gen + 1u) * nloc) {
;             __builtin_amdgcn_fence(__ATOMIC_RELEASE, "agent");
;             asm volatile("s_waitcnt vmcnt(0)" ::: "memory");
;             const unsigned og = xb_add(&bar[XB_TOP], 1u);
;             const unsigned tg = og / nx;
;             if (og + 1u == (tg + 1u) * nx) xb_add(&bar[XB_TOPGEN], 1u);
;             else XB_SPIN(xb_ld(&bar[XB_TOPGEN]) == tg, bar);
;             __builtin_amdgcn_fence(__ATOMIC_ACQUIRE, "agent");
;             xb_add(&bar[XB_XGEN(b.x)], 1u);
;             asm volatile("s_waitcnt vmcnt(0)" ::: "memory");
;         } else {
;             XB_SPIN(xb_ld(&bar[XB_XGEN(b.x)]) == gen, bar);
.LBB0_1269:
	s_or_b64 exec, exec, s[22:23]
	v_cvt_f32_u32_e32 v4, v2
	s_waitcnt vmcnt(0)
	v_readfirstlane_b32 s0, v3
	v_sub_u32_e32 v3, 0, v2
	v_rcp_iflag_f32_e32 v4, v4
	v_add_u32_e32 v5, s0, v1
	v_mul_f32_e32 v4, 0x4f7ffffe, v4
	v_cvt_u32_f32_e32 v4, v4
	v_mul_lo_u32 v1, v3, v4
	v_mul_hi_u32 v1, v4, v1
	v_add_u32_e32 v1, v4, v1
	v_mul_hi_u32 v1, v5, v1
	v_mul_lo_u32 v3, v1, v2
	v_sub_u32_e32 v3, v5, v3
	v_add_u32_e32 v4, 1, v1
	v_cmp_ge_u32_e32 vcc, v3, v2
	s_nop 1
	v_cndmask_b32_e32 v1, v1, v4, vcc
	v_sub_u32_e32 v4, v3, v2
	v_cndmask_b32_e32 v3, v3, v4, vcc
	v_add_u32_e32 v4, 1, v1
	v_cmp_ge_u32_e32 vcc, v3, v2
	v_add_u32_e32 v3, 1, v5
	s_nop 0
	v_cndmask_b32_e32 v1, v1, v4, vcc
	v_mul_lo_u32 v4, v2, v1
	v_add_u32_e32 v2, v4, v2
	v_cmp_ne_u32_e32 vcc, v3, v2
	s_and_saveexec_b64 s[12:13], vcc
	s_xor_b64 s[20:21], exec, s[12:13]
	s_cbranch_execz .LBB0_1283
	s_waitcnt lgkmcnt(0)
	v_mov_b32_e32 v0, 0x7000
	global_load_dword v0, v0, s[16:17] offset:1280 sc1
	s_add_u32 s26, s16, 0x7500
	s_addc_u32 s27, s17, 0
	s_waitcnt vmcnt(0)
	v_cmp_eq_u32_e32 vcc, v0, v1
	s_and_saveexec_b64 s[22:23], vcc
	s_cbranch_execz .LBB0_1282
	s_add_u32 s24, s16, 0x4200
	s_addc_u32 s25, s17, 0
	s_mov_b32 s0, 1
	s_mov_b64 s[42:43], 0
	v_mov_b32_e32 v0, 0
	s_branch .LBB0_1273

; __device__ __forceinline__ unsigned xb_ld(unsigned* p)              { return __hip_atomic_load(p, __ATOMIC_RELAXED, __HIP_MEMORY_SCOPE_AGENT); }
; __device__ __forceinline__ unsigned xb_add(unsigned* p, unsigned v) { return __hip_atomic_fetch_add(p, v, __ATOMIC_RELAXED, __HIP_MEMORY_SCOPE_AGENT); }
; #define XB_SPIN(cond, bar) do { unsigned _sp = 0; while (cond) { __builtin_amdgcn_s_sleep(1); \
;     if ((++_sp & 255u) == 0u) { if (xb_ld(&(bar)[XB_TMO])) break; if (_sp > XB_SPIN_CAP) { atomicAdd(&(bar)[XB_TMO], 1u); break; } } } } while (0)
; __device__ __forceinline__ void xcd_barrier(const XcdBarrier& b) {
;     ...
;         const unsigned old = xb_add(&bar[XB_XSUB(b.x)], 1u);
;         const unsigned gen = old / nloc;
;         if (old + 1u == (gen + 1u) * nloc) {
;             __builtin_amdgcn_fence(__ATOMIC_RELEASE, "agent");
;             asm volatile("s_waitcnt vmcnt(0)" ::: "memory");
;             const unsigned og = xb_add(&bar[XB_TOP], 1u);
;             const unsigned tg = og / nx;
;             if (og + 1u == (tg + 1u) * nx) xb_add(&bar[XB_TOPGEN], 1u);
;             else XB_SPIN(xb_ld(&bar[XB_TOPGEN]) == tg, bar);
;             __builtin_amdgcn_fence(__ATOMIC_ACQUIRE, "agent");
;             xb_add(&bar[XB_XGEN(b.x)], 1u);
;             asm volatile("s_waitcnt vmcnt(0)" ::: "memory");
;         } else {
;             XB_SPIN(xb_ld(&bar[XB_XGEN(b.x)]) == gen, bar);
.LBB0_1451:
	s_or_b64 exec, exec, s[20:21]
	v_cvt_f32_u32_e32 v4, v2
	s_waitcnt vmcnt(0)
	v_readfirstlane_b32 s0, v3
	v_sub_u32_e32 v3, 0, v2
	v_rcp_iflag_f32_e32 v4, v4
	v_add_u32_e32 v5, s0, v1
	v_mul_f32_e32 v4, 0x4f7ffffe, v4
	v_cvt_u32_f32_e32 v4, v4
	v_mul_lo_u32 v1, v3, v4
	v_mul_hi_u32 v1, v4, v1
	v_add_u32_e32 v1, v4, v1
	v_mul_hi_u32 v1, v5, v1
	v_mul_lo_u32 v3, v1, v2
	v_sub_u32_e32 v3, v5, v3
	v_add_u32_e32 v4, 1, v1
	v_cmp_ge_u32_e32 vcc, v3, v2
	s_nop 1
	v_cndmask_b32_e32 v1, v1, v4, vcc
	v_sub_u32_e32 v4, v3, v2
	v_cndmask_b32_e32 v3, v3, v4, vcc
	v_add_u32_e32 v4, 1, v1
	v_cmp_ge_u32_e32 vcc, v3, v2
	v_add_u32_e32 v3, 1, v5
	s_nop 0
	v_cndmask_b32_e32 v1, v1, v4, vcc
	v_mul_lo_u32 v4, v2, v1
	v_add_u32_e32 v2, v4, v2
	v_cmp_ne_u32_e32 vcc, v3, v2
	s_and_saveexec_b64 s[6:7], vcc
	s_xor_b64 s[18:19], exec, s[6:7]
	s_cbranch_execz .LBB0_1465
	s_waitcnt lgkmcnt(0)
	v_mov_b32_e32 v0, 0x7000
	global_load_dword v0, v0, s[14:15] offset:1280 sc1
	s_add_u32 s24, s14, 0x7500
	s_addc_u32 s25, s15, 0
	s_waitcnt vmcnt(0)
	v_cmp_eq_u32_e32 vcc, v0, v1
	s_and_saveexec_b64 s[20:21], vcc
	s_cbranch_execz .LBB0_1464
	s_add_u32 s22, s14, 0x4200
	s_addc_u32 s23, s15, 0
	s_mov_b32 s0, 1
	s_mov_b64 s[26:27], 0
	v_mov_b32_e32 v0, 0
	s_branch .LBB0_1455

; __device__ __forceinline__ unsigned xb_ld(unsigned* p)              { return __hip_atomic_load(p, __ATOMIC_RELAXED, __HIP_MEMORY_SCOPE_AGENT); }
; __device__ __forceinline__ unsigned xb_add(unsigned* p, unsigned v) { return __hip_atomic_fetch_add(p, v, __ATOMIC_RELAXED, __HIP_MEMORY_SCOPE_AGENT); }
; #define XB_SPIN(cond, bar) do { unsigned _sp = 0; while (cond) { __builtin_amdgcn_s_sleep(1); \
;     if ((++_sp & 255u) == 0u) { if (xb_ld(&(bar)[XB_TMO])) break; if (_sp > XB_SPIN_CAP) { atomicAdd(&(bar)[XB_TMO], 1u); break; } } } } while (0)
; __device__ __forceinline__ void xcd_barrier(const XcdBarrier& b) {
;     ...
;         const unsigned old = xb_add(&bar[XB_XSUB(b.x)], 1u);
;         const unsigned gen = old / nloc;
;         if (old + 1u == (gen + 1u) * nloc) {
;             __builtin_amdgcn_fence(__ATOMIC_RELEASE, "agent");
;             asm volatile("s_waitcnt vmcnt(0)" ::: "memory");
;             const unsigned og = xb_add(&bar[XB_TOP], 1u);
;             const unsigned tg = og / nx;
;             if (og + 1u == (tg + 1u) * nx) xb_add(&bar[XB_TOPGEN], 1u);
;             else XB_SPIN(xb_ld(&bar[XB_TOPGEN]) == tg, bar);
;             __builtin_amdgcn_fence(__ATOMIC_ACQUIRE, "agent");
;             xb_add(&bar[XB_XGEN(b.x)], 1u);
;             asm volatile("s_waitcnt vmcnt(0)" ::: "memory");
;         } else {
;             XB_SPIN(xb_ld(&bar[XB_XGEN(b.x)]) == gen, bar);
.LBB0_1797:
	s_or_b64 exec, exec, s[18:19]
	v_cvt_f32_u32_e32 v4, v2
	s_waitcnt vmcnt(0)
	v_readfirstlane_b32 s0, v3
	v_sub_u32_e32 v3, 0, v2
	v_rcp_iflag_f32_e32 v4, v4
	v_add_u32_e32 v5, s0, v1
	v_mul_f32_e32 v4, 0x4f7ffffe, v4
	v_cvt_u32_f32_e32 v4, v4
	v_mul_lo_u32 v1, v3, v4
	v_mul_hi_u32 v1, v4, v1
	v_add_u32_e32 v1, v4, v1
	v_mul_hi_u32 v1, v5, v1
	v_mul_lo_u32 v3, v1, v2
	v_sub_u32_e32 v3, v5, v3
	v_add_u32_e32 v4, 1, v1
	v_cmp_ge_u32_e32 vcc, v3, v2
	s_nop 1
	v_cndmask_b32_e32 v1, v1, v4, vcc
	v_sub_u32_e32 v4, v3, v2
	v_cndmask_b32_e32 v3, v3, v4, vcc
	v_add_u32_e32 v4, 1, v1
	v_cmp_ge_u32_e32 vcc, v3, v2
	v_add_u32_e32 v3, 1, v5
	s_nop 0
	v_cndmask_b32_e32 v1, v1, v4, vcc
	v_mul_lo_u32 v4, v2, v1
	v_add_u32_e32 v2, v4, v2
	v_cmp_ne_u32_e32 vcc, v3, v2
	s_and_saveexec_b64 s[12:13], vcc
	s_xor_b64 s[16:17], exec, s[12:13]
	s_cbranch_execz .LBB0_1811
	s_waitcnt lgkmcnt(0)
	v_mov_b32_e32 v0, 0x7000
	global_load_dword v0, v0, s[8:9] offset:1280 sc1
	s_add_u32 s22, s8, 0x7500
	s_addc_u32 s23, s9, 0
	s_waitcnt vmcnt(0)
	v_cmp_eq_u32_e32 vcc, v0, v1
	s_and_saveexec_b64 s[18:19], vcc
	s_cbranch_execz .LBB0_1810
	s_add_u32 s20, s8, 0x4200
	s_addc_u32 s21, s9, 0
	s_mov_b32 s0, 1
	s_mov_b64 s[24:25], 0
	v_mov_b32_e32 v0, 0
	s_branch .LBB0_1801

; __device__ __forceinline__ unsigned xb_ld(unsigned* p)              { return __hip_atomic_load(p, __ATOMIC_RELAXED, __HIP_MEMORY_SCOPE_AGENT); }
; __device__ __forceinline__ unsigned xb_add(unsigned* p, unsigned v) { return __hip_atomic_fetch_add(p, v, __ATOMIC_RELAXED, __HIP_MEMORY_SCOPE_AGENT); }
; #define XB_SPIN(cond, bar) do { unsigned _sp = 0; while (cond) { __builtin_amdgcn_s_sleep(1); \
;     if ((++_sp & 255u) == 0u) { if (xb_ld(&(bar)[XB_TMO])) break; if (_sp > XB_SPIN_CAP) { atomicAdd(&(bar)[XB_TMO], 1u); break; } } } } while (0)
; __device__ __forceinline__ void xcd_barrier(const XcdBarrier& b) {
;     ...
;         const unsigned old = xb_add(&bar[XB_XSUB(b.x)], 1u);
;         const unsigned gen = old / nloc;
;         if (old + 1u == (gen + 1u) * nloc) {
;             __builtin_amdgcn_fence(__ATOMIC_RELEASE, "agent");
;             asm volatile("s_waitcnt vmcnt(0)" ::: "memory");
;             const unsigned og = xb_add(&bar[XB_TOP], 1u);
;             const unsigned tg = og / nx;
;             if (og + 1u == (tg + 1u) * nx) xb_add(&bar[XB_TOPGEN], 1u);
;             else XB_SPIN(xb_ld(&bar[XB_TOPGEN]) == tg, bar);
;             __builtin_amdgcn_fence(__ATOMIC_ACQUIRE, "agent");
;             xb_add(&bar[XB_XGEN(b.x)], 1u);
;             asm volatile("s_waitcnt vmcnt(0)" ::: "memory");
;         } else {
;             XB_SPIN(xb_ld(&bar[XB_XGEN(b.x)]) == gen, bar);
.LBB0_1903:
	s_or_b64 exec, exec, s[16:17]
	v_cvt_f32_u32_e32 v4, v2
	s_waitcnt vmcnt(0)
	v_readfirstlane_b32 s0, v3
	v_sub_u32_e32 v3, 0, v2
	v_rcp_iflag_f32_e32 v4, v4
	v_add_u32_e32 v5, s0, v1
	v_mul_f32_e32 v4, 0x4f7ffffe, v4
	v_cvt_u32_f32_e32 v4, v4
	v_mul_lo_u32 v1, v3, v4
	v_mul_hi_u32 v1, v4, v1
	v_add_u32_e32 v1, v4, v1
	v_mul_hi_u32 v1, v5, v1
	v_mul_lo_u32 v3, v1, v2
	v_sub_u32_e32 v3, v5, v3
	v_add_u32_e32 v4, 1, v1
	v_cmp_ge_u32_e32 vcc, v3, v2
	s_nop 1
	v_cndmask_b32_e32 v1, v1, v4, vcc
	v_sub_u32_e32 v4, v3, v2
	v_cndmask_b32_e32 v3, v3, v4, vcc
	v_add_u32_e32 v4, 1, v1
	v_cmp_ge_u32_e32 vcc, v3, v2
	v_add_u32_e32 v3, 1, v5
	s_nop 0
	v_cndmask_b32_e32 v1, v1, v4, vcc
	v_mul_lo_u32 v4, v2, v1
	v_add_u32_e32 v2, v4, v2
	v_cmp_ne_u32_e32 vcc, v3, v2
	s_and_saveexec_b64 s[0:1], vcc
	s_xor_b64 s[14:15], exec, s[0:1]
	s_cbranch_execz .LBB0_1917
	s_waitcnt lgkmcnt(0)
	v_mov_b32_e32 v0, 0x7000
	global_load_dword v0, v0, s[8:9] offset:1280 sc1
	s_add_u32 s20, s8, 0x7500
	s_addc_u32 s21, s9, 0
	s_waitcnt vmcnt(0)
	v_cmp_eq_u32_e32 vcc, v0, v1
	s_and_saveexec_b64 s[16:17], vcc
	s_cbranch_execz .LBB0_1916
	s_add_u32 s18, s8, 0x4200
	s_addc_u32 s19, s9, 0
	s_mov_b32 s0, 1
	s_mov_b64 s[22:23], 0
	v_mov_b32_e32 v0, 0
	s_branch .LBB0_1907

; __device__ __forceinline__ unsigned xb_ld(unsigned* p)              { return __hip_atomic_load(p, __ATOMIC_RELAXED, __HIP_MEMORY_SCOPE_AGENT); }
; __device__ __forceinline__ unsigned xb_add(unsigned* p, unsigned v) { return __hip_atomic_fetch_add(p, v, __ATOMIC_RELAXED, __HIP_MEMORY_SCOPE_AGENT); }
; #define XB_SPIN(cond, bar) do { unsigned _sp = 0; while (cond) { __builtin_amdgcn_s_sleep(1); \
;     if ((++_sp & 255u) == 0u) { if (xb_ld(&(bar)[XB_TMO])) break; if (_sp > XB_SPIN_CAP) { atomicAdd(&(bar)[XB_TMO], 1u); break; } } } } while (0)
; __device__ __forceinline__ void xcd_barrier(const XcdBarrier& b) {
;     ...
;         const unsigned old = xb_add(&bar[XB_XSUB(b.x)], 1u);
;         const unsigned gen = old / nloc;
;         if (old + 1u == (gen + 1u) * nloc) {
;             __builtin_amdgcn_fence(__ATOMIC_RELEASE, "agent");
;             asm volatile("s_waitcnt vmcnt(0)" ::: "memory");
;             const unsigned og = xb_add(&bar[XB_TOP], 1u);
;             const unsigned tg = og / nx;
;             if (og + 1u == (tg + 1u) * nx) xb_add(&bar[XB_TOPGEN], 1u);
;             else XB_SPIN(xb_ld(&bar[XB_TOPGEN]) == tg, bar);
;             __builtin_amdgcn_fence(__ATOMIC_ACQUIRE, "agent");
;             xb_add(&bar[XB_XGEN(b.x)], 1u);
;             asm volatile("s_waitcnt vmcnt(0)" ::: "memory");
;         } else {
;             XB_SPIN(xb_ld(&bar[XB_XGEN(b.x)]) == gen, bar);
.LBB0_2065:
	s_or_b64 exec, exec, s[14:15]
	v_cvt_f32_u32_e32 v4, v2
	s_waitcnt vmcnt(0)
	v_readfirstlane_b32 s0, v3
	v_sub_u32_e32 v3, 0, v2
	v_rcp_iflag_f32_e32 v4, v4
	v_add_u32_e32 v5, s0, v1
	v_mul_f32_e32 v4, 0x4f7ffffe, v4
	v_cvt_u32_f32_e32 v4, v4
	v_mul_lo_u32 v1, v3, v4
	v_mul_hi_u32 v1, v4, v1
	v_add_u32_e32 v1, v4, v1
	v_mul_hi_u32 v1, v5, v1
	v_mul_lo_u32 v3, v1, v2
	v_sub_u32_e32 v3, v5, v3
	v_add_u32_e32 v4, 1, v1
	v_cmp_ge_u32_e32 vcc, v3, v2
	s_nop 1
	v_cndmask_b32_e32 v1, v1, v4, vcc
	v_sub_u32_e32 v4, v3, v2
	v_cndmask_b32_e32 v3, v3, v4, vcc
	v_add_u32_e32 v4, 1, v1
	v_cmp_ge_u32_e32 vcc, v3, v2
	v_add_u32_e32 v3, 1, v5
	s_nop 0
	v_cndmask_b32_e32 v1, v1, v4, vcc
	v_mul_lo_u32 v4, v2, v1
	v_add_u32_e32 v2, v4, v2
	v_cmp_ne_u32_e32 vcc, v3, v2
	s_and_saveexec_b64 s[0:1], vcc
	s_xor_b64 s[12:13], exec, s[0:1]
	s_cbranch_execz .LBB0_2079
	s_waitcnt lgkmcnt(0)
	v_mov_b32_e32 v0, 0x7000
	global_load_dword v0, v0, s[8:9] offset:1280 sc1
	s_add_u32 s18, s8, 0x7500
	s_addc_u32 s19, s9, 0
	s_waitcnt vmcnt(0)
	v_cmp_eq_u32_e32 vcc, v0, v1
	s_and_saveexec_b64 s[14:15], vcc
	s_cbranch_execz .LBB0_2078
	s_add_u32 s16, s8, 0x4200
	s_addc_u32 s17, s9, 0
	s_mov_b32 s0, 1
	s_mov_b64 s[20:21], 0
	v_mov_b32_e32 v0, 0
	s_branch .LBB0_2069
